# stack + combine phase: the eight per-row gate loads of a tile issued at the tile top
# baseline (speedup 1.0000x reference)
; #define LAS __attribute__((address_space(3)))
; __device__ __forceinline__ float silu_f(float v) { return v * __builtin_amdgcn_rcpf(1.f + __builtin_amdgcn_exp2f(-1.4426950408889634f * v)); }
; __device__ __forceinline__ v4u pack8(const float (&f)[8]) { v4u o; o.x = pk2(f[0], f[1]); o.y = pk2(f[2], f[3]); o.z = pk2(f[4], f[5]); o.w = pk2(f[6], f[7]); return o; }
; __device__ __forceinline__ void phase_combine(int l, LAS unsigned char* lds, int G) {
;     ...
;         for (int i = 0; i < 16; ++i) { const int cc = 32 * wave + 2 * i + (lane >> 5), tl = 2 * (lane & 31);
;             *(LAS unsigned*)(yt + cc * YTP + tl) = *(const unsigned*)(YT + ((size_t)cc * BATCH + b) * SEQ + t0 + tl); }
;         __syncthreads();
; #pragma unroll
;         for (int r = 0; r < 4; ++r) {
;             const bf16r* pr = base + (size_t)r * DIN; const size_t row = row0 + tl0 + r;
;             bf16r* yrow = Y + row * DMODEL + c;
;             float g[8], o[8], y[8];
;             { unpack8(*(const v4u*)(pr + C_BG), g); float xa[8], xb[8], xc[8]; unpack8(xw[r], xa); unpack8(xw[r + 1], xb); unpack8(xw[r + 2], xc);
; #pragma unroll
;               for (int e = 0; e < 8; ++e) { const float x0 = cw[c + e] * xa[e] + cw[768 + c + e] * xb[e] + cw[1536 + c + e] * xc[e] + cbv[c + e];
;                   y[e] = silu_f(g[e]) * x0 * bf1(yt[(c + e) * YTP + tl0 + r]); }
;               *(v4u*)(yrow + 256) = pack8(y); }
;             { unpack8(*(const v4u*)(pr + C_DP), o);
; #pragma unroll
;               for (int e = 0; e < 8; ++e) y[e] = o[e] * (scw[c + e] * uw[r][e] + scw[256 + c + e] * uw[r + 1][e] + scw[512 + c + e] * uw[r + 2][e]);
;               *(v4u*)(yrow + 768) = pack8(y); }
.LBB0_603:
	s_or_b64 exec, exec, s[0:1]
	s_ashr_i32 s0, s15, 6
	s_ashr_i32 s1, s0, 31
	s_lshl_b64 s[0:1], s[0:1], 13
	s_add_u32 s0, s2, s0
	s_addc_u32 s1, s3, s1
	s_lshl_b32 s16, s16, 1
	s_add_u32 s0, s0, s16
	s_addc_u32 s1, s1, 0
	v_lshl_add_u64 v[98:99], s[0:1], 0, v[0:1]
	v_lshl_add_u64 v[100:101], v[98:99], 0, v[60:61]
	v_lshl_add_u64 v[102:103], v[98:99], 0, v[58:59]
	v_lshl_add_u64 v[104:105], v[98:99], 0, v[62:63]
	v_lshl_add_u64 v[106:107], v[98:99], 0, v[64:65]
	v_lshl_add_u64 v[114:115], v[98:99], 0, v[72:73]
	v_lshl_add_u64 v[108:109], v[98:99], 0, v[66:67]
	v_lshl_add_u64 v[110:111], v[98:99], 0, v[68:69]
	v_lshl_add_u64 v[112:113], v[98:99], 0, v[70:71]
	global_load_dword v116, v[100:101], off
	global_load_dword v117, v[102:103], off
	global_load_dword v118, v[104:105], off
	global_load_dword v119, v[106:107], off
	global_load_dword v120, v[108:109], off
	global_load_dword v121, v[110:111], off
	global_load_dword v122, v[112:113], off
	s_nop 0
	global_load_dword v114, v[114:115], off
	v_lshl_add_u64 v[100:101], v[98:99], 0, v[74:75]
	v_lshl_add_u64 v[102:103], v[98:99], 0, v[76:77]
	v_lshl_add_u64 v[104:105], v[98:99], 0, v[78:79]
	v_lshl_add_u64 v[106:107], v[98:99], 0, v[80:81]
	v_lshl_add_u64 v[108:109], v[98:99], 0, v[82:83]
	v_lshl_add_u64 v[110:111], v[98:99], 0, v[84:85]
	v_lshl_add_u64 v[112:113], v[98:99], 0, v[86:87]
	v_lshl_add_u64 v[98:99], v[98:99], 0, v[88:89]
	global_load_dword v100, v[100:101], off
	s_nop 0
	global_load_dword v101, v[102:103], off
	s_nop 0
	global_load_dword v102, v[104:105], off
	global_load_dword v103, v[106:107], off
	s_nop 0
	global_load_dword v104, v[108:109], off
	global_load_dword v105, v[110:111], off
	global_load_dword v106, v[112:113], off
	global_load_dword v107, v[98:99], off
	s_mov_b32 s0, 0x6000000
	v_add_co_u32_e32 v98, vcc, s0, v96
	s_waitcnt vmcnt(17)
	v_and_b32_e32 v125, 0xffff0000, v19
	v_addc_co_u32_e32 v99, vcc, 0, v97, vcc
	v_and_b32_e32 v124, 0xffff0000, v18
	v_and_b32_e32 v177, 0xffff0000, v15
	v_and_b32_e32 v176, 0xffff0000, v14
	v_lshlrev_b32_e32 v179, 16, v17
	v_lshlrev_b32_e32 v178, 16, v16
	v_lshlrev_b32_e32 v127, 16, v19
	v_lshlrev_b32_e32 v126, 16, v18
	v_lshlrev_b32_e32 v123, 16, v15
	v_lshlrev_b32_e32 v108, 16, v46
	v_lshlrev_b32_e32 v109, 16, v47
	v_and_b32_e32 v181, 0xffff0000, v17
	v_and_b32_e32 v180, 0xffff0000, v16
	s_brev_b32 s0, 64
	s_add_i32 s15, s15, s52
	s_waitcnt vmcnt(15)
	ds_write_b32 v138, v116
	s_waitcnt vmcnt(14)
	ds_write_b32 v139, v117
	s_waitcnt vmcnt(13)
	ds_write_b32 v140, v118
	s_waitcnt vmcnt(12)
	ds_write_b32 v141, v119
	s_waitcnt vmcnt(11)
	ds_write_b32 v142, v120
	s_waitcnt vmcnt(10)
	ds_write_b32 v143, v121
	s_waitcnt vmcnt(9)
	ds_write_b32 v144, v122
	s_waitcnt vmcnt(8)
	ds_write_b32 v145, v114
	s_waitcnt vmcnt(7)
	ds_write_b32 v146, v100
	s_waitcnt vmcnt(6)
	ds_write_b32 v147, v101
	s_waitcnt vmcnt(5)
	ds_write_b32 v148, v102
	s_waitcnt vmcnt(4)
	ds_write_b32 v149, v103
	s_waitcnt vmcnt(3)
	ds_write_b32 v150, v104
	s_waitcnt vmcnt(2)
	ds_write_b32 v151, v105
	s_waitcnt vmcnt(1)
	ds_write_b32 v152, v106
	s_waitcnt vmcnt(0)
	ds_write_b32 v153, v107
	s_waitcnt lgkmcnt(0)
	s_barrier
	v_mov_b64_e32 v[110:111], v[210:211]
	v_mov_b64_e32 v[112:113], v[212:213]
	global_load_dwordx4 v[114:117], v[50:51], off
	global_load_dwordx4 v[128:131], v[50:51], off offset:3072
	global_load_dwordx4 v[132:135], v[52:53], off
	global_load_dwordx4 v[156:159], v[54:55], off
	global_load_dwordx4 v[160:163], v[50:51], off offset:16
	global_load_dwordx4 v[164:167], v[50:51], off offset:3088
	global_load_dwordx4 v[168:171], v[52:53], off offset:16
	global_load_dwordx4 v[172:175], v[54:55], off offset:16
	v_lshlrev_b32_e32 v121, 16, v21
	v_lshlrev_b32_e32 v120, 16, v20
	v_and_b32_e32 v106, 0xffff0000, v46
	v_and_b32_e32 v107, 0xffff0000, v47
	v_lshlrev_b32_e32 v104, 16, v48
	v_lshlrev_b32_e32 v105, 16, v49
	v_lshlrev_b32_e32 v122, 16, v14
	v_and_b32_e32 v119, 0xffff0000, v21
	v_and_b32_e32 v118, 0xffff0000, v20
	v_and_b32_e32 v102, 0xffff0000, v48
	v_and_b32_e32 v103, 0xffff0000, v49
	ds_read2_b64 v[18:21], v154 offset1:33
	ds_read2_b64 v[14:17], v154 offset0:66 offset1:99
	ds_read2_b32 v[98:99], v154 offset0:33 offset1:34
	ds_read2_b32 v[100:101], v154 offset0:99 offset1:100
	ds_read2_b32 v[46:47], v154 offset0:165 offset1:166
	ds_read2_b32 v[48:49], v154 offset0:231 offset1:232
	s_waitcnt lgkmcnt(5)
	v_lshlrev_b32_e32 v183, 16, v20
	v_lshlrev_b32_e32 v182, 16, v18
	s_waitcnt lgkmcnt(2)
	v_lshlrev_b32_e32 v185, 16, v100
	v_lshlrev_b32_e32 v184, 16, v98
	s_waitcnt vmcnt(8)
	v_lshlrev_b32_e32 v187, 16, v111
	v_lshlrev_b32_e32 v186, 16, v110
	v_and_b32_e32 v111, 0xffff0000, v111
	v_and_b32_e32 v110, 0xffff0000, v110
	s_waitcnt vmcnt(7)
	v_mov_b32_e32 v188, v114
	v_mov_b32_e32 v189, v116
	s_waitcnt vmcnt(6)
	v_mov_b32_e32 v203, v130
	s_waitcnt vmcnt(5)
	v_mov_b32_e32 v204, v132
	v_mov_b32_e32 v205, v134
	v_mov_b32_e32 v116, v115
	v_mov_b32_e32 v130, v129
	v_mov_b32_e32 v134, v133
	v_lshlrev_b32_e32 v115, 16, v113
	v_lshlrev_b32_e32 v114, 16, v112
	s_waitcnt vmcnt(3)
	v_mov_b32_e32 v129, v162
	s_waitcnt vmcnt(2)
	v_mov_b32_e32 v132, v164
	v_mov_b32_e32 v133, v166
	v_mul_f32_e32 v155, 0xbfb8aa3b, v186
	v_mul_f32_e32 v162, 0xbfb8aa3b, v187
	v_mov_b32_e32 v202, v128
	v_mov_b32_e32 v207, v158
	v_mov_b32_e32 v158, v157
	v_mov_b32_e32 v128, v160
	s_waitcnt vmcnt(1)
; __device__ __forceinline__ float silu_f(float v) { return v * __builtin_amdgcn_rcpf(1.f + __builtin_amdgcn_exp2f(-1.4426950408889634f * v)); }
; __device__ __forceinline__ v4u pack8(const float (&f)[8]) { v4u o; o.x = pk2(f[0], f[1]); o.y = pk2(f[2], f[3]); o.z = pk2(f[4], f[5]); o.w = pk2(f[6], f[7]); return o; }
; __device__ __forceinline__ void phase_combine(int l, LAS unsigned char* lds, int G) {
;     ...
;         for (int r = 0; r < 4; ++r) {
;             const bf16r* pr = base + (size_t)r * DIN; const size_t row = row0 + tl0 + r;
;             bf16r* yrow = Y + row * DMODEL + c;
;             float g[8], o[8], y[8];
;             { unpack8(*(const v4u*)(pr + C_BG), g); float xa[8], xb[8], xc[8]; unpack8(xw[r], xa); unpack8(xw[r + 1], xb); unpack8(xw[r + 2], xc);
; #pragma unroll
;               for (int e = 0; e < 8; ++e) { const float x0 = cw[c + e] * xa[e] + cw[768 + c + e] * xb[e] + cw[1536 + c + e] * xc[e] + cbv[c + e];
;                   y[e] = silu_f(g[e]) * x0 * bf1(yt[(c + e) * YTP + tl0 + r]); }
;               *(v4u*)(yrow + 256) = pack8(y); }
;             { unpack8(*(const v4u*)(pr + C_DP), o);
; #pragma unroll
;               for (int e = 0; e < 8; ++e) y[e] = o[e] * (scw[c + e] * uw[r][e] + scw[256 + c + e] * uw[r + 1][e] + scw[512 + c + e] * uw[r + 2][e]);
;               *(v4u*)(yrow + 768) = pack8(y); }
	v_mov_b32_e32 v157, v170
	v_mul_f32_e32 v160, 0xbfb8aa3b, v110
	v_pk_mul_f32 v[130:131], v[130:131], v[124:125]
	v_mul_f32_e32 v164, 0xbfb8aa3b, v111
	v_mul_f32_e32 v166, 0xbfb8aa3b, v114
	v_pk_mul_f32 v[132:133], v[132:133], v[120:121]
	v_mul_f32_e32 v170, 0xbfb8aa3b, v115
	v_exp_f32_e32 v155, v155
	v_exp_f32_e32 v162, v162
	v_exp_f32_e32 v160, v160
	v_pk_fma_f32 v[116:117], v[116:117], v[176:177], v[130:131]
	v_exp_f32_e32 v130, v164
	v_exp_f32_e32 v131, v166
	v_pk_fma_f32 v[128:129], v[128:129], v[178:179], v[132:133]
	v_exp_f32_e32 v132, v170
	v_mov_b32_e32 v206, v156
	v_mov_b32_e32 v156, v168
	v_pk_fma_f32 v[116:117], v[134:135], v[106:107], v[116:117]
	v_add_f32_e32 v133, 1.0, v155
	v_add_f32_e32 v135, 1.0, v162
	v_pk_fma_f32 v[128:129], v[156:157], v[104:105], v[128:129]
	v_pk_add_f32 v[116:117], v[158:159], v[116:117]
	v_add_f32_e32 v134, 1.0, v160
	v_add_f32_e32 v155, 1.0, v130
	v_add_f32_e32 v156, 1.0, v131
	v_add_f32_e32 v158, 1.0, v132
	v_rcp_f32_e32 v130, v133
	v_rcp_f32_e32 v131, v135
	v_pk_mul_f32 v[202:203], v[202:203], v[126:127]
	v_rcp_f32_e32 v132, v134
	v_rcp_f32_e32 v133, v155
	v_rcp_f32_e32 v134, v156
	v_rcp_f32_e32 v135, v158
	v_pk_fma_f32 v[122:123], v[188:189], v[122:123], v[202:203]
	s_waitcnt vmcnt(0)
	v_mov_b32_e32 v208, v172
	v_pk_fma_f32 v[122:123], v[204:205], v[108:109], v[122:123]
	v_mov_b32_e32 v209, v174
	v_pk_add_f32 v[122:123], v[206:207], v[122:123]
	v_pk_mul_f32 v[130:131], v[130:131], v[186:187]
	v_pk_add_f32 v[128:129], v[208:209], v[128:129]
	v_pk_mul_f32 v[110:111], v[132:133], v[110:111]
	v_pk_mul_f32 v[114:115], v[134:135], v[114:115]
	v_pk_mul_f32 v[122:123], v[122:123], v[130:131]
	v_and_b32_e32 v113, 0xffff0000, v113
	v_and_b32_e32 v112, 0xffff0000, v112
	v_pk_mul_f32 v[110:111], v[110:111], v[116:117]
	v_pk_mul_f32 v[114:115], v[114:115], v[128:129]
	v_pk_mul_f32 v[116:117], v[122:123], v[182:183]
	v_lshlrev_b32_e32 v123, 16, v16
	v_lshlrev_b32_e32 v122, 16, v14
	v_mul_f32_e32 v168, 0xbfb8aa3b, v112
	v_pk_mul_f32 v[114:115], v[114:115], v[122:123]
	v_mul_f32_e32 v122, 0xbfb8aa3b, v113
	v_exp_f32_e32 v164, v168
	v_exp_f32_e32 v128, v122
	v_mov_b32_e32 v166, v165
	v_mov_b32_e32 v162, v161
	v_add_f32_e32 v157, 1.0, v164
	v_add_f32_e32 v128, 1.0, v128
	v_rcp_f32_e32 v156, v157
	v_rcp_f32_e32 v157, v128
	v_pk_mul_f32 v[122:123], v[166:167], v[118:119]
	v_mov_b32_e32 v170, v169
	v_pk_fma_f32 v[122:123], v[162:163], v[180:181], v[122:123]
	v_mov_b32_e32 v174, v173
	v_pk_fma_f32 v[122:123], v[170:171], v[102:103], v[122:123]
	v_pk_mul_f32 v[112:113], v[156:157], v[112:113]
	v_pk_add_f32 v[122:123], v[174:175], v[122:123]
	v_pk_mul_f32 v[110:111], v[110:111], v[184:185]
	v_pk_mul_f32 v[112:113], v[112:113], v[122:123]
	s_waitcnt lgkmcnt(0)
	v_lshlrev_b32_e32 v123, 16, v48
	v_lshlrev_b32_e32 v122, 16, v46
	v_pk_mul_f32 v[112:113], v[112:113], v[122:123]
	v_bfe_u32 v128, v111, 16, 1
	v_bfe_u32 v122, v113, 16, 1
	v_bfe_u32 v123, v112, 16, 1
	v_add3_u32 v112, v112, v123, s72
	v_add3_u32 v113, v113, v122, s72
	v_bfe_u32 v122, v116, 16, 1
	v_bfe_u32 v123, v117, 16, 1
	v_bfe_u32 v129, v110, 16, 1
	v_add3_u32 v117, v117, v123, s72
	v_add3_u32 v116, v116, v122, s72
	v_add3_u32 v110, v110, v129, s72
	v_add3_u32 v111, v111, v128, s72
	v_bfe_u32 v128, v114, 16, 1
	v_bfe_u32 v129, v115, 16, 1
	v_lshrrev_b32_e32 v116, 16, v116
	v_lshrrev_b32_e32 v117, 16, v117
	v_add3_u32 v115, v115, v129, s72
	v_add3_u32 v114, v114, v128, s72
	v_and_or_b32 v111, v111, s55, v117
	v_and_or_b32 v110, v110, s55, v116
	v_lshl_add_u64 v[116:117], v[94:95], 0, v[90:91]
	v_lshrrev_b32_e32 v114, 16, v114
	v_lshrrev_b32_e32 v115, 16, v115
	v_add_co_u32_e32 v122, vcc, s0, v116
	v_and_or_b32 v113, v113, s55, v115
	v_and_or_b32 v112, v112, s55, v114
	v_addc_co_u32_e32 v123, vcc, 0, v117, vcc
	s_mov_b32 s0, 0x6001000
	global_store_dwordx4 v[122:123], v[110:113], off offset:512
	v_lshlrev_b32_e32 v135, 16, v35
	v_lshlrev_b32_e32 v134, 16, v34
	v_add_co_u32_e32 v110, vcc, s0, v96
	v_and_b32_e32 v133, 0xffff0000, v35
	s_nop 0
	v_addc_co_u32_e32 v111, vcc, 0, v97, vcc
	v_mov_b64_e32 v[156:157], v[214:215]
	v_mov_b64_e32 v[158:159], v[216:217]
	global_load_dwordx4 v[160:163], v[56:57], off
	global_load_dwordx4 v[164:167], v[56:57], off offset:1024
	global_load_dwordx4 v[168:171], v[56:57], off offset:2048
	global_load_dwordx4 v[172:175], v[56:57], off offset:16
	global_load_dwordx4 v[176:179], v[56:57], off offset:1040
	global_load_dwordx4 v[180:183], v[56:57], off offset:2064
	v_and_b32_e32 v132, 0xffff0000, v34
	v_lshlrev_b32_e32 v35, 16, v31
	v_lshlrev_b32_e32 v34, 16, v30
	v_lshlrev_b32_e32 v115, 16, v43
	v_lshlrev_b32_e32 v114, 16, v42
	v_and_b32_e32 v113, 0xffff0000, v43
	v_and_b32_e32 v112, 0xffff0000, v42
	v_lshlrev_b32_e32 v111, 16, v45
	v_lshlrev_b32_e32 v110, 16, v44
	v_and_b32_e32 v43, 0xffff0000, v45
	v_and_b32_e32 v42, 0xffff0000, v44
	v_and_b32_e32 v31, 0xffff0000, v31
	v_and_b32_e32 v30, 0xffff0000, v30
	v_lshlrev_b32_e32 v131, 16, v37
	v_lshlrev_b32_e32 v130, 16, v36
	v_and_b32_e32 v129, 0xffff0000, v37
	v_and_b32_e32 v128, 0xffff0000, v36
	v_lshlrev_b32_e32 v37, 16, v33
	v_lshlrev_b32_e32 v36, 16, v32
	v_and_b32_e32 v33, 0xffff0000, v33
	v_and_b32_e32 v32, 0xffff0000, v32
	s_mov_b32 s0, 0x6002000
	s_waitcnt vmcnt(6)
	v_lshlrev_b32_e32 v45, 16, v157
	s_waitcnt vmcnt(5)
	v_mov_b32_e32 v184, v160
	s_waitcnt vmcnt(4)
	v_mov_b32_e32 v186, v164
	v_mov_b32_e32 v187, v166
	v_mov_b32_e32 v185, v162
	v_pk_mul_f32 v[186:187], v[186:187], v[134:135]
	v_lshlrev_b32_e32 v44, 16, v156
	v_pk_fma_f32 v[34:35], v[184:185], v[34:35], v[186:187]
	s_waitcnt vmcnt(3)
; __device__ __forceinline__ float silu_f(float v) { return v * __builtin_amdgcn_rcpf(1.f + __builtin_amdgcn_exp2f(-1.4426950408889634f * v)); }
; __device__ __forceinline__ v4u pack8(const float (&f)[8]) { v4u o; o.x = pk2(f[0], f[1]); o.y = pk2(f[2], f[3]); o.z = pk2(f[4], f[5]); o.w = pk2(f[6], f[7]); return o; }
; __device__ __forceinline__ void phase_combine(int l, LAS unsigned char* lds, int G) {
;     ...
;         for (int r = 0; r < 4; ++r) {
;             const bf16r* pr = base + (size_t)r * DIN; const size_t row = row0 + tl0 + r;
;             bf16r* yrow = Y + row * DMODEL + c;
;             float g[8], o[8], y[8];
;             { unpack8(*(const v4u*)(pr + C_BG), g); float xa[8], xb[8], xc[8]; unpack8(xw[r], xa); unpack8(xw[r + 1], xb); unpack8(xw[r + 2], xc);
; #pragma unroll
;               for (int e = 0; e < 8; ++e) { const float x0 = cw[c + e] * xa[e] + cw[768 + c + e] * xb[e] + cw[1536 + c + e] * xc[e] + cbv[c + e];
;                   y[e] = silu_f(g[e]) * x0 * bf1(yt[(c + e) * YTP + tl0 + r]); }
;               *(v4u*)(yrow + 256) = pack8(y); }
;             { unpack8(*(const v4u*)(pr + C_DP), o);
; #pragma unroll
;               for (int e = 0; e < 8; ++e) y[e] = o[e] * (scw[c + e] * uw[r][e] + scw[256 + c + e] * uw[r + 1][e] + scw[512 + c + e] * uw[r + 2][e]);
;               *(v4u*)(yrow + 768) = pack8(y); }
	v_mov_b32_e32 v184, v168
	v_mov_b32_e32 v185, v170
	v_pk_fma_f32 v[34:35], v[184:185], v[114:115], v[34:35]
	v_mov_b32_e32 v166, v165
	v_pk_mul_f32 v[34:35], v[34:35], v[44:45]
	v_mov_b32_e32 v162, v161
	v_pk_mul_f32 v[44:45], v[166:167], v[132:133]
	v_mov_b32_e32 v170, v169
	v_pk_fma_f32 v[30:31], v[162:163], v[30:31], v[44:45]
	v_and_b32_e32 v157, 0xffff0000, v157
	v_and_b32_e32 v156, 0xffff0000, v156
	v_pk_fma_f32 v[30:31], v[170:171], v[112:113], v[30:31]
	s_waitcnt vmcnt(1)
	v_mov_b32_e32 v160, v176
	v_mov_b32_e32 v161, v178
	v_pk_mul_f32 v[30:31], v[30:31], v[156:157]
	v_lshlrev_b32_e32 v45, 16, v159
	v_lshlrev_b32_e32 v44, 16, v158
	v_and_b32_e32 v157, 0xffff0000, v159
	v_and_b32_e32 v156, 0xffff0000, v158
	v_mov_b32_e32 v158, v172
	v_mov_b32_e32 v159, v174
	v_pk_mul_f32 v[160:161], v[160:161], v[130:131]
	v_mov_b32_e32 v178, v177
	v_pk_fma_f32 v[36:37], v[158:159], v[36:37], v[160:161]
	s_waitcnt vmcnt(0)
	v_mov_b32_e32 v158, v180
	v_mov_b32_e32 v159, v182
	v_pk_fma_f32 v[36:37], v[158:159], v[110:111], v[36:37]
	v_mov_b32_e32 v174, v173
	v_pk_mul_f32 v[36:37], v[36:37], v[44:45]
	v_pk_mul_f32 v[44:45], v[178:179], v[128:129]
	v_mov_b32_e32 v182, v181
	v_pk_fma_f32 v[32:33], v[174:175], v[32:33], v[44:45]
	v_bfe_u32 v155, v31, 16, 1
	v_pk_fma_f32 v[32:33], v[182:183], v[42:43], v[32:33]
	v_add3_u32 v31, v31, v155, s72
	v_pk_mul_f32 v[32:33], v[32:33], v[156:157]
	v_bfe_u32 v156, v30, 16, 1
	v_bfe_u32 v44, v33, 16, 1
	v_bfe_u32 v45, v32, 16, 1
	v_add3_u32 v30, v30, v156, s72
	v_add3_u32 v32, v32, v45, s72
	v_add3_u32 v33, v33, v44, s72
	v_bfe_u32 v44, v34, 16, 1
	v_bfe_u32 v45, v35, 16, 1
	v_bfe_u32 v155, v36, 16, 1
	v_bfe_u32 v156, v37, 16, 1
	v_add3_u32 v37, v37, v156, s72
	v_add3_u32 v36, v36, v155, s72
	v_add3_u32 v35, v35, v45, s72
	v_add3_u32 v34, v34, v44, s72
	v_lshrrev_b32_e32 v34, 16, v34
	v_lshrrev_b32_e32 v35, 16, v35
	v_lshrrev_b32_e32 v36, 16, v36
	v_lshrrev_b32_e32 v37, 16, v37
	v_and_or_b32 v33, v33, s55, v37
	v_and_or_b32 v32, v32, s55, v36
	v_and_or_b32 v31, v31, s55, v35
	v_and_or_b32 v30, v30, s55, v34
	global_store_dwordx4 v[122:123], v[30:33], off offset:1536
	v_lshlrev_b32_e32 v44, 16, v38
	v_and_b32_e32 v34, 0xffff0000, v38
	v_add_co_u32_e32 v30, vcc, s0, v96
	v_lshlrev_b32_e32 v45, 16, v39
	s_nop 0
	v_addc_co_u32_e32 v31, vcc, 0, v97, vcc
	v_mov_b64_e32 v[156:157], v[228:229]
	v_mov_b64_e32 v[158:159], v[230:231]
	global_load_dwordx4 v[160:163], v[50:51], off
	global_load_dwordx4 v[164:167], v[50:51], off offset:3072
	global_load_dwordx4 v[168:171], v[52:53], off
	global_load_dwordx4 v[172:175], v[54:55], off
	global_load_dwordx4 v[176:179], v[50:51], off offset:16
	global_load_dwordx4 v[180:183], v[50:51], off offset:3088
	global_load_dwordx4 v[184:187], v[52:53], off offset:16
	v_and_b32_e32 v35, 0xffff0000, v39
	global_load_dwordx4 v[36:39], v[54:55], off offset:16
	v_lshlrev_b32_e32 v32, 16, v40
	v_and_b32_e32 v30, 0xffff0000, v40
	v_lshlrev_b32_e32 v33, 16, v41
	v_and_b32_e32 v31, 0xffff0000, v41
	s_mov_b32 s0, 0x6003000
	s_waitcnt vmcnt(8)
	v_lshlrev_b32_e32 v40, 16, v156
	v_and_b32_e32 v156, 0xffff0000, v156
	v_mul_f32_e32 v155, 0xbfb8aa3b, v40
	v_exp_f32_e32 v155, v155
	v_mul_f32_e32 v188, 0xbfb8aa3b, v156
	v_exp_f32_e32 v189, v188
	v_lshlrev_b32_e32 v41, 16, v157
	v_add_f32_e32 v155, 1.0, v155
	v_rcp_f32_e32 v188, v155
	v_add_f32_e32 v155, 1.0, v189
	v_rcp_f32_e32 v202, v155
	v_mul_f32_e32 v155, 0xbfb8aa3b, v41
	v_exp_f32_e32 v155, v155
	s_waitcnt vmcnt(6)
	v_mov_b32_e32 v206, v164
	v_mov_b32_e32 v207, v166
	v_mov_b32_e32 v204, v160
	v_add_f32_e32 v155, 1.0, v155
	v_rcp_f32_e32 v189, v155
	v_mov_b32_e32 v205, v162
	v_pk_mul_f32 v[206:207], v[206:207], v[108:109]
	v_and_b32_e32 v157, 0xffff0000, v157
	v_pk_fma_f32 v[126:127], v[204:205], v[126:127], v[206:207]
	s_waitcnt vmcnt(5)
	v_mov_b32_e32 v204, v168
	v_mov_b32_e32 v205, v170
	v_pk_fma_f32 v[126:127], v[204:205], v[44:45], v[126:127]
	s_waitcnt vmcnt(4)
	v_mov_b32_e32 v204, v172
	v_mov_b32_e32 v205, v174
	v_pk_add_f32 v[126:127], v[204:205], v[126:127]
	v_pk_mul_f32 v[40:41], v[188:189], v[40:41]
	v_mov_b32_e32 v166, v165
	v_pk_mul_f32 v[40:41], v[126:127], v[40:41]
	v_and_b32_e32 v126, 0xffff0000, v18
	v_mul_f32_e32 v18, 0xbfb8aa3b, v157
	v_exp_f32_e32 v18, v18
	v_and_b32_e32 v127, 0xffff0000, v20
	v_pk_mul_f32 v[40:41], v[40:41], v[126:127]
	v_mov_b32_e32 v162, v161
	v_add_f32_e32 v18, 1.0, v18
	v_rcp_f32_e32 v203, v18
	v_pk_mul_f32 v[126:127], v[166:167], v[106:107]
	v_mov_b32_e32 v170, v169
	v_pk_fma_f32 v[124:125], v[162:163], v[124:125], v[126:127]
	v_mov_b32_e32 v174, v173
	v_pk_fma_f32 v[124:125], v[170:171], v[34:35], v[124:125]
	v_pk_mul_f32 v[126:127], v[202:203], v[156:157]
	v_pk_add_f32 v[124:125], v[174:175], v[124:125]
	v_and_b32_e32 v156, 0xffff0000, v158
	v_pk_mul_f32 v[124:125], v[126:127], v[124:125]
	v_and_b32_e32 v127, 0xffff0000, v100
	v_and_b32_e32 v126, 0xffff0000, v98
	v_pk_mul_f32 v[124:125], v[124:125], v[126:127]
	v_lshlrev_b32_e32 v126, 16, v158
	v_mul_f32_e32 v18, 0xbfb8aa3b, v126
	v_exp_f32_e32 v18, v18
	v_mul_f32_e32 v20, 0xbfb8aa3b, v156
	v_exp_f32_e32 v20, v20
	v_lshlrev_b32_e32 v127, 16, v159
	v_add_f32_e32 v18, 1.0, v18
	v_rcp_f32_e32 v158, v18
	v_add_f32_e32 v18, 1.0, v20
	v_rcp_f32_e32 v160, v18
	v_mul_f32_e32 v18, 0xbfb8aa3b, v127
	v_exp_f32_e32 v18, v18
	v_and_b32_e32 v157, 0xffff0000, v159
	s_waitcnt vmcnt(2)
	v_mov_b32_e32 v164, v180
	v_mov_b32_e32 v165, v182
	v_add_f32_e32 v18, 1.0, v18
	v_rcp_f32_e32 v159, v18
	v_mov_b32_e32 v162, v176
	v_mov_b32_e32 v163, v178
	v_pk_mul_f32 v[164:165], v[164:165], v[104:105]
	v_pk_mul_f32 v[126:127], v[158:159], v[126:127]
	v_pk_fma_f32 v[120:121], v[162:163], v[120:121], v[164:165]
	s_waitcnt vmcnt(1)
; __device__ __forceinline__ float silu_f(float v) { return v * __builtin_amdgcn_rcpf(1.f + __builtin_amdgcn_exp2f(-1.4426950408889634f * v)); }
; __device__ __forceinline__ v4u pack8(const float (&f)[8]) { v4u o; o.x = pk2(f[0], f[1]); o.y = pk2(f[2], f[3]); o.z = pk2(f[4], f[5]); o.w = pk2(f[6], f[7]); return o; }
; __device__ __forceinline__ void phase_combine(int l, LAS unsigned char* lds, int G) {
;     ...
;         for (int r = 0; r < 4; ++r) {
;             const bf16r* pr = base + (size_t)r * DIN; const size_t row = row0 + tl0 + r;
;             bf16r* yrow = Y + row * DMODEL + c;
;             float g[8], o[8], y[8];
;             { unpack8(*(const v4u*)(pr + C_BG), g); float xa[8], xb[8], xc[8]; unpack8(xw[r], xa); unpack8(xw[r + 1], xb); unpack8(xw[r + 2], xc);
; #pragma unroll
;               for (int e = 0; e < 8; ++e) { const float x0 = cw[c + e] * xa[e] + cw[768 + c + e] * xb[e] + cw[1536 + c + e] * xc[e] + cbv[c + e];
;                   y[e] = silu_f(g[e]) * x0 * bf1(yt[(c + e) * YTP + tl0 + r]); }
;               *(v4u*)(yrow + 256) = pack8(y); }
;             { unpack8(*(const v4u*)(pr + C_DP), o);
; #pragma unroll
;               for (int e = 0; e < 8; ++e) y[e] = o[e] * (scw[c + e] * uw[r][e] + scw[256 + c + e] * uw[r + 1][e] + scw[512 + c + e] * uw[r + 2][e]);
;               *(v4u*)(yrow + 768) = pack8(y); }
	v_mov_b32_e32 v162, v184
	v_mov_b32_e32 v163, v186
	v_pk_fma_f32 v[120:121], v[162:163], v[32:33], v[120:121]
	s_waitcnt vmcnt(0)
	v_mov_b32_e32 v162, v36
	v_mov_b32_e32 v163, v38
	v_pk_add_f32 v[120:121], v[162:163], v[120:121]
	v_mov_b32_e32 v182, v181
	v_pk_mul_f32 v[120:121], v[126:127], v[120:121]
	v_and_b32_e32 v126, 0xffff0000, v14
	v_mul_f32_e32 v14, 0xbfb8aa3b, v157
	v_exp_f32_e32 v14, v14
	v_and_b32_e32 v127, 0xffff0000, v16
	v_pk_mul_f32 v[120:121], v[120:121], v[126:127]
	v_mov_b32_e32 v178, v177
	v_add_f32_e32 v14, 1.0, v14
	v_rcp_f32_e32 v161, v14
	v_pk_mul_f32 v[126:127], v[182:183], v[102:103]
	v_mov_b32_e32 v186, v185
	v_pk_fma_f32 v[118:119], v[178:179], v[118:119], v[126:127]
	v_mov_b32_e32 v38, v37
	v_pk_fma_f32 v[118:119], v[186:187], v[30:31], v[118:119]
	v_bfe_u32 v18, v125, 16, 1
	v_pk_add_f32 v[36:37], v[38:39], v[118:119]
	v_pk_mul_f32 v[38:39], v[160:161], v[156:157]
	v_bfe_u32 v20, v124, 16, 1
	v_pk_mul_f32 v[36:37], v[38:39], v[36:37]
	v_and_b32_e32 v39, 0xffff0000, v48
	v_and_b32_e32 v38, 0xffff0000, v46
	v_pk_mul_f32 v[36:37], v[36:37], v[38:39]
	v_bfe_u32 v38, v120, 16, 1
	v_bfe_u32 v14, v37, 16, 1
	v_bfe_u32 v16, v36, 16, 1
	v_add3_u32 v16, v36, v16, s72
	v_add3_u32 v14, v37, v14, s72
	v_bfe_u32 v36, v40, 16, 1
	v_bfe_u32 v37, v41, 16, 1
	v_bfe_u32 v39, v121, 16, 1
	v_add3_u32 v39, v121, v39, s72
	v_add3_u32 v38, v120, v38, s72
	v_add3_u32 v37, v41, v37, s72
	v_add3_u32 v36, v40, v36, s72
	v_add3_u32 v20, v124, v20, s72
	v_add3_u32 v18, v125, v18, s72
	v_lshrrev_b32_e32 v36, 16, v36
	v_lshrrev_b32_e32 v37, 16, v37
	v_lshrrev_b32_e32 v38, 16, v38
	v_lshrrev_b32_e32 v39, 16, v39
	v_and_or_b32 v39, v14, s55, v39
	v_and_or_b32 v38, v16, s55, v38
	v_and_or_b32 v37, v18, s55, v37
	v_and_or_b32 v36, v20, s55, v36
	global_store_dwordx4 v[122:123], v[36:39], off offset:2560
	v_lshlrev_b32_e32 v41, 16, v27
	v_lshlrev_b32_e32 v40, 16, v26
	v_add_co_u32_e32 v36, vcc, s0, v96
	v_and_b32_e32 v39, 0xffff0000, v27
	s_nop 0
	v_addc_co_u32_e32 v37, vcc, 0, v97, vcc
	v_mov_b64_e32 v[118:119], v[232:233]
	v_mov_b64_e32 v[120:121], v[234:235]
	global_load_dwordx4 v[124:127], v[56:57], off
	global_load_dwordx4 v[156:159], v[56:57], off offset:1024
	global_load_dwordx4 v[160:163], v[56:57], off offset:2048
	global_load_dwordx4 v[164:167], v[56:57], off offset:16
	global_load_dwordx4 v[168:171], v[56:57], off offset:1040
	global_load_dwordx4 v[172:175], v[56:57], off offset:2064
	v_and_b32_e32 v38, 0xffff0000, v26
	v_lshlrev_b32_e32 v37, 16, v29
	v_lshlrev_b32_e32 v36, 16, v28
	v_and_b32_e32 v27, 0xffff0000, v29
	v_and_b32_e32 v26, 0xffff0000, v28
	s_mov_b32 s0, 0x6004000
	s_waitcnt vmcnt(6)
	v_lshlrev_b32_e32 v29, 16, v119
	s_waitcnt vmcnt(5)
	v_mov_b32_e32 v176, v124
	s_waitcnt vmcnt(4)
	v_mov_b32_e32 v179, v158
	v_mov_b32_e32 v158, v157
	v_mov_b32_e32 v177, v126
	v_mov_b32_e32 v178, v156
	v_mov_b32_e32 v126, v125
	v_pk_mul_f32 v[124:125], v[158:159], v[112:113]
	v_pk_mul_f32 v[178:179], v[178:179], v[114:115]
	v_pk_fma_f32 v[124:125], v[126:127], v[132:133], v[124:125]
	s_waitcnt vmcnt(1)
	v_mov_b32_e32 v132, v168
	v_mov_b32_e32 v133, v170
	v_pk_fma_f32 v[134:135], v[176:177], v[134:135], v[178:179]
	v_mov_b32_e32 v177, v162
	v_mov_b32_e32 v162, v161
	v_mov_b32_e32 v126, v164
	v_mov_b32_e32 v127, v166
	v_pk_mul_f32 v[132:133], v[132:133], v[110:111]
	v_lshlrev_b32_e32 v28, 16, v118
	v_and_b32_e32 v119, 0xffff0000, v119
	v_and_b32_e32 v118, 0xffff0000, v118
	v_pk_fma_f32 v[124:125], v[162:163], v[38:39], v[124:125]
	v_pk_fma_f32 v[126:127], v[126:127], v[130:131], v[132:133]
	s_waitcnt vmcnt(0)
	v_mov_b32_e32 v130, v172
	v_mov_b32_e32 v131, v174
	v_pk_mul_f32 v[118:119], v[124:125], v[118:119]
	v_lshlrev_b32_e32 v125, 16, v121
	v_lshlrev_b32_e32 v124, 16, v120
	v_pk_fma_f32 v[126:127], v[130:131], v[36:37], v[126:127]
	v_mov_b32_e32 v170, v169
	v_mov_b32_e32 v176, v160
	v_pk_mul_f32 v[124:125], v[126:127], v[124:125]
	v_mov_b32_e32 v166, v165
	v_pk_mul_f32 v[126:127], v[170:171], v[42:43]
	v_pk_fma_f32 v[134:135], v[176:177], v[40:41], v[134:135]
	v_pk_fma_f32 v[126:127], v[166:167], v[128:129], v[126:127]
	v_mov_b32_e32 v174, v173
	v_pk_mul_f32 v[28:29], v[134:135], v[28:29]
	v_and_b32_e32 v121, 0xffff0000, v121
	v_and_b32_e32 v120, 0xffff0000, v120
	v_pk_fma_f32 v[126:127], v[174:175], v[26:27], v[126:127]
	v_bfe_u32 v46, v28, 16, 1
	v_pk_mul_f32 v[120:121], v[126:127], v[120:121]
	v_bfe_u32 v48, v29, 16, 1
	v_bfe_u32 v98, v124, 16, 1
	v_bfe_u32 v100, v125, 16, 1
	v_bfe_u32 v14, v121, 16, 1
	v_bfe_u32 v16, v120, 16, 1
	v_bfe_u32 v18, v119, 16, 1
	v_bfe_u32 v20, v118, 16, 1
	v_add3_u32 v100, v125, v100, s72
	v_add3_u32 v98, v124, v98, s72
	v_add3_u32 v29, v29, v48, s72
	v_add3_u32 v28, v28, v46, s72
	v_add3_u32 v20, v118, v20, s72
	v_add3_u32 v18, v119, v18, s72
	v_add3_u32 v16, v120, v16, s72
	v_add3_u32 v14, v121, v14, s72
	v_lshrrev_b32_e32 v28, 16, v28
	v_lshrrev_b32_e32 v29, 16, v29
	v_lshrrev_b32_e32 v46, 16, v98
	v_lshrrev_b32_e32 v48, 16, v100
	v_and_or_b32 v121, v14, s55, v48
	v_and_or_b32 v120, v16, s55, v46
	v_and_or_b32 v119, v18, s55, v29
	v_and_or_b32 v118, v20, s55, v28
	v_add_co_u32_e32 v28, vcc, s0, v96
	global_store_dwordx4 v[122:123], v[118:121], off offset:3584
	s_nop 0
	v_addc_co_u32_e32 v29, vcc, 0, v97, vcc
	v_mov_b64_e32 v[122:123], v[236:237]
	v_mov_b64_e32 v[124:125], v[238:239]
	global_load_dwordx4 v[126:129], v[50:51], off
	global_load_dwordx4 v[130:133], v[50:51], off offset:3072
	global_load_dwordx4 v[156:159], v[52:53], off
	global_load_dwordx4 v[160:163], v[54:55], off
	global_load_dwordx4 v[164:167], v[50:51], off offset:16
	global_load_dwordx4 v[168:171], v[50:51], off offset:3088
	global_load_dwordx4 v[172:175], v[52:53], off offset:16
	global_load_dwordx4 v[176:179], v[54:55], off offset:16
	v_lshlrev_b32_e32 v120, 16, v22
	v_and_b32_e32 v118, 0xffff0000, v22
	v_lshlrev_b32_e32 v28, 16, v24
	v_and_b32_e32 v22, 0xffff0000, v24
	v_lshlrev_b32_e32 v121, 16, v23
	v_and_b32_e32 v119, 0xffff0000, v23
	v_lshlrev_b32_e32 v29, 16, v25
	v_and_b32_e32 v23, 0xffff0000, v25
	s_mov_b32 s0, 0x2001000
	s_waitcnt vmcnt(8)
; __device__ __forceinline__ float silu_f(float v) { return v * __builtin_amdgcn_rcpf(1.f + __builtin_amdgcn_exp2f(-1.4426950408889634f * v)); }
; __device__ __forceinline__ v4u pack8(const float (&f)[8]) { v4u o; o.x = pk2(f[0], f[1]); o.y = pk2(f[2], f[3]); o.z = pk2(f[4], f[5]); o.w = pk2(f[6], f[7]); return o; }
; __device__ __forceinline__ void phase_combine(int l, LAS unsigned char* lds, int G) {
;     ...
;         for (int r = 0; r < 4; ++r) {
;             const bf16r* pr = base + (size_t)r * DIN; const size_t row = row0 + tl0 + r;
;             bf16r* yrow = Y + row * DMODEL + c;
;             float g[8], o[8], y[8];
;             { unpack8(*(const v4u*)(pr + C_BG), g); float xa[8], xb[8], xc[8]; unpack8(xw[r], xa); unpack8(xw[r + 1], xb); unpack8(xw[r + 2], xc);
; #pragma unroll
;               for (int e = 0; e < 8; ++e) { const float x0 = cw[c + e] * xa[e] + cw[768 + c + e] * xb[e] + cw[1536 + c + e] * xc[e] + cbv[c + e];
;                   y[e] = silu_f(g[e]) * x0 * bf1(yt[(c + e) * YTP + tl0 + r]); }
;               *(v4u*)(yrow + 256) = pack8(y); }
;             { unpack8(*(const v4u*)(pr + C_DP), o);
; #pragma unroll
;               for (int e = 0; e < 8; ++e) y[e] = o[e] * (scw[c + e] * uw[r][e] + scw[256 + c + e] * uw[r + 1][e] + scw[512 + c + e] * uw[r + 2][e]);
;               *(v4u*)(yrow + 768) = pack8(y); }
	v_lshlrev_b32_e32 v24, 16, v122
	v_and_b32_e32 v122, 0xffff0000, v122
	v_mul_f32_e32 v14, 0xbfb8aa3b, v24
	v_exp_f32_e32 v14, v14
	v_mul_f32_e32 v16, 0xbfb8aa3b, v122
	v_exp_f32_e32 v16, v16
	v_lshlrev_b32_e32 v25, 16, v123
	v_add_f32_e32 v14, 1.0, v14
	v_rcp_f32_e32 v134, v14
	v_add_f32_e32 v14, 1.0, v16
	v_rcp_f32_e32 v180, v14
	v_mul_f32_e32 v14, 0xbfb8aa3b, v25
	v_exp_f32_e32 v14, v14
	v_and_b32_e32 v123, 0xffff0000, v123
	s_waitcnt vmcnt(6)
	v_mov_b32_e32 v184, v130
	v_mov_b32_e32 v185, v132
	v_add_f32_e32 v14, 1.0, v14
	v_rcp_f32_e32 v135, v14
	v_mul_f32_e32 v14, 0xbfb8aa3b, v123
	v_exp_f32_e32 v14, v14
	v_mov_b32_e32 v182, v126
	v_mov_b32_e32 v183, v128
	v_pk_mul_f32 v[184:185], v[184:185], v[44:45]
	v_pk_mul_f32 v[24:25], v[134:135], v[24:25]
	v_pk_fma_f32 v[108:109], v[182:183], v[108:109], v[184:185]
	s_waitcnt vmcnt(5)
	v_mov_b32_e32 v182, v156
	v_mov_b32_e32 v183, v158
	v_pk_fma_f32 v[108:109], v[182:183], v[120:121], v[108:109]
	s_waitcnt vmcnt(4)
	v_mov_b32_e32 v182, v160
	v_mov_b32_e32 v183, v162
	v_pk_add_f32 v[108:109], v[182:183], v[108:109]
	v_add_f32_e32 v14, 1.0, v14
	v_pk_mul_f32 v[24:25], v[108:109], v[24:25]
	v_lshlrev_b32_e32 v109, 16, v21
	v_lshlrev_b32_e32 v108, 16, v19
	v_mov_b32_e32 v132, v131
	v_rcp_f32_e32 v181, v14
	v_pk_mul_f32 v[24:25], v[24:25], v[108:109]
	v_mov_b32_e32 v128, v127
	v_pk_mul_f32 v[108:109], v[132:133], v[34:35]
	v_mov_b32_e32 v158, v157
	v_pk_fma_f32 v[106:107], v[128:129], v[106:107], v[108:109]
	v_mov_b32_e32 v162, v161
	v_pk_fma_f32 v[106:107], v[158:159], v[118:119], v[106:107]
	v_pk_mul_f32 v[108:109], v[180:181], v[122:123]
	v_pk_add_f32 v[106:107], v[162:163], v[106:107]
	v_and_b32_e32 v122, 0xffff0000, v124
	v_pk_mul_f32 v[106:107], v[108:109], v[106:107]
	v_lshlrev_b32_e32 v109, 16, v101
	v_lshlrev_b32_e32 v108, 16, v99
	v_pk_mul_f32 v[106:107], v[106:107], v[108:109]
	v_lshlrev_b32_e32 v108, 16, v124
	v_mul_f32_e32 v14, 0xbfb8aa3b, v108
	v_exp_f32_e32 v14, v14
	v_mul_f32_e32 v16, 0xbfb8aa3b, v122
	v_exp_f32_e32 v16, v16
	v_lshlrev_b32_e32 v109, 16, v125
	v_add_f32_e32 v14, 1.0, v14
	v_rcp_f32_e32 v124, v14
	v_add_f32_e32 v14, 1.0, v16
	v_rcp_f32_e32 v126, v14
	v_mul_f32_e32 v14, 0xbfb8aa3b, v109
	v_exp_f32_e32 v14, v14
	v_and_b32_e32 v123, 0xffff0000, v125
	s_waitcnt vmcnt(2)
	v_mov_b32_e32 v130, v168
	v_mov_b32_e32 v131, v170
	v_add_f32_e32 v14, 1.0, v14
	v_rcp_f32_e32 v125, v14
	v_mul_f32_e32 v14, 0xbfb8aa3b, v123
	v_exp_f32_e32 v14, v14
	v_mov_b32_e32 v128, v164
	v_mov_b32_e32 v129, v166
	v_pk_mul_f32 v[130:131], v[130:131], v[32:33]
	v_pk_mul_f32 v[108:109], v[124:125], v[108:109]
	v_pk_fma_f32 v[104:105], v[128:129], v[104:105], v[130:131]
	s_waitcnt vmcnt(1)
	v_mov_b32_e32 v128, v172
	v_mov_b32_e32 v129, v174
	v_pk_fma_f32 v[104:105], v[128:129], v[28:29], v[104:105]
	s_waitcnt vmcnt(0)
	v_mov_b32_e32 v128, v176
	v_mov_b32_e32 v129, v178
	v_pk_add_f32 v[104:105], v[128:129], v[104:105]
	v_add_f32_e32 v14, 1.0, v14
	v_pk_mul_f32 v[104:105], v[108:109], v[104:105]
	v_lshlrev_b32_e32 v109, 16, v17
	v_lshlrev_b32_e32 v108, 16, v15
	v_mov_b32_e32 v170, v169
	v_rcp_f32_e32 v127, v14
	v_pk_mul_f32 v[104:105], v[104:105], v[108:109]
	v_mov_b32_e32 v166, v165
	v_pk_mul_f32 v[108:109], v[170:171], v[30:31]
	v_mov_b32_e32 v174, v173
	v_pk_fma_f32 v[102:103], v[166:167], v[102:103], v[108:109]
	v_mov_b32_e32 v178, v177
	v_pk_fma_f32 v[102:103], v[174:175], v[22:23], v[102:103]
	v_pk_mul_f32 v[108:109], v[126:127], v[122:123]
	v_pk_add_f32 v[102:103], v[178:179], v[102:103]
	v_bfe_u32 v46, v24, 16, 1
	v_pk_mul_f32 v[102:103], v[108:109], v[102:103]
	v_lshlrev_b32_e32 v109, 16, v49
	v_lshlrev_b32_e32 v108, 16, v47
	v_pk_mul_f32 v[102:103], v[102:103], v[108:109]
	v_bfe_u32 v20, v106, 16, 1
	v_bfe_u32 v48, v25, 16, 1
	v_bfe_u32 v98, v104, 16, 1
	v_bfe_u32 v100, v105, 16, 1
	v_add3_u32 v24, v24, v46, s72
	v_bfe_u32 v14, v103, 16, 1
	v_bfe_u32 v16, v102, 16, 1
	v_bfe_u32 v18, v107, 16, 1
	v_add3_u32 v20, v106, v20, s72
	v_add3_u32 v100, v105, v100, s72
	v_add3_u32 v98, v104, v98, s72
	v_add3_u32 v25, v25, v48, s72
	v_lshrrev_b32_e32 v24, 16, v24
	v_add3_u32 v18, v107, v18, s72
	v_add3_u32 v16, v102, v16, s72
	v_add3_u32 v14, v103, v14, s72
	v_lshrrev_b32_e32 v25, 16, v25
	v_lshrrev_b32_e32 v46, 16, v98
	v_lshrrev_b32_e32 v48, 16, v100
	v_and_or_b32 v102, v20, s55, v24
	v_add_co_u32_e32 v24, vcc, s0, v116
	v_and_or_b32 v105, v14, s55, v48
	v_and_or_b32 v104, v16, s55, v46
	v_and_or_b32 v103, v18, s55, v25
	v_addc_co_u32_e32 v25, vcc, 0, v117, vcc
	s_mov_b32 s0, 0x6005000
	global_store_dwordx4 v[24:25], v[102:105], off offset:512
	v_lshlrev_b32_e32 v107, 16, v11
	v_lshlrev_b32_e32 v106, 16, v10
	v_add_co_u32_e32 v102, vcc, s0, v96
	v_and_b32_e32 v105, 0xffff0000, v11
	s_nop 0
	v_addc_co_u32_e32 v103, vcc, 0, v97, vcc
	v_mov_b64_e32 v[122:123], v[240:241]
	v_mov_b64_e32 v[124:125], v[242:243]
	global_load_dwordx4 v[126:129], v[56:57], off
	global_load_dwordx4 v[130:133], v[56:57], off offset:1024
	global_load_dwordx4 v[156:159], v[56:57], off offset:2048
	global_load_dwordx4 v[160:163], v[56:57], off offset:16
	global_load_dwordx4 v[164:167], v[56:57], off offset:1040
	global_load_dwordx4 v[168:171], v[56:57], off offset:2064
	v_and_b32_e32 v104, 0xffff0000, v10
	v_lshlrev_b32_e32 v103, 16, v13
	v_lshlrev_b32_e32 v102, 16, v12
	v_and_b32_e32 v11, 0xffff0000, v13
	v_and_b32_e32 v10, 0xffff0000, v12
	s_mov_b32 s0, 0x6006000
	v_and_b32_e32 v21, 0xffff0000, v21
	v_and_b32_e32 v17, 0xffff0000, v17
	s_waitcnt vmcnt(6)
	v_lshlrev_b32_e32 v13, 16, v123
	v_lshlrev_b32_e32 v12, 16, v122
	v_and_b32_e32 v109, 0xffff0000, v123
	v_and_b32_e32 v108, 0xffff0000, v122
	s_waitcnt vmcnt(4)
; __device__ __forceinline__ float silu_f(float v) { return v * __builtin_amdgcn_rcpf(1.f + __builtin_amdgcn_exp2f(-1.4426950408889634f * v)); }
; __device__ __forceinline__ v4u pack8(const float (&f)[8]) { v4u o; o.x = pk2(f[0], f[1]); o.y = pk2(f[2], f[3]); o.z = pk2(f[4], f[5]); o.w = pk2(f[6], f[7]); return o; }
; __device__ __forceinline__ void phase_combine(int l, LAS unsigned char* lds, int G) {
;     ...
;         for (int r = 0; r < 4; ++r) {
;             const bf16r* pr = base + (size_t)r * DIN; const size_t row = row0 + tl0 + r;
;             bf16r* yrow = Y + row * DMODEL + c;
;             float g[8], o[8], y[8];
;             { unpack8(*(const v4u*)(pr + C_BG), g); float xa[8], xb[8], xc[8]; unpack8(xw[r], xa); unpack8(xw[r + 1], xb); unpack8(xw[r + 2], xc);
; #pragma unroll
;               for (int e = 0; e < 8; ++e) { const float x0 = cw[c + e] * xa[e] + cw[768 + c + e] * xb[e] + cw[1536 + c + e] * xc[e] + cbv[c + e];
;                   y[e] = silu_f(g[e]) * x0 * bf1(yt[(c + e) * YTP + tl0 + r]); }
;               *(v4u*)(yrow + 256) = pack8(y); }
;             { unpack8(*(const v4u*)(pr + C_DP), o);
; #pragma unroll
;               for (int e = 0; e < 8; ++e) y[e] = o[e] * (scw[c + e] * uw[r][e] + scw[256 + c + e] * uw[r + 1][e] + scw[512 + c + e] * uw[r + 2][e]);
;               *(v4u*)(yrow + 768) = pack8(y); }
	v_mov_b32_e32 v122, v130
	v_mov_b32_e32 v123, v132
	v_mov_b32_e32 v116, v126
	v_mov_b32_e32 v117, v128
	v_pk_mul_f32 v[122:123], v[122:123], v[40:41]
	v_mov_b32_e32 v132, v131
	v_pk_fma_f32 v[114:115], v[116:117], v[114:115], v[122:123]
	s_waitcnt vmcnt(3)
	v_mov_b32_e32 v116, v156
	v_mov_b32_e32 v117, v158
	v_pk_fma_f32 v[114:115], v[116:117], v[106:107], v[114:115]
	v_mov_b32_e32 v128, v127
	v_pk_mul_f32 v[12:13], v[114:115], v[12:13]
	v_pk_mul_f32 v[114:115], v[132:133], v[38:39]
	s_waitcnt vmcnt(1)
	v_mov_b32_e32 v122, v164
	v_mov_b32_e32 v123, v166
	v_pk_fma_f32 v[112:113], v[128:129], v[112:113], v[114:115]
	v_mov_b32_e32 v158, v157
	v_mov_b32_e32 v116, v160
	v_mov_b32_e32 v117, v162
	v_pk_mul_f32 v[122:123], v[122:123], v[36:37]
	v_pk_fma_f32 v[112:113], v[158:159], v[104:105], v[112:113]
	v_pk_fma_f32 v[110:111], v[116:117], v[110:111], v[122:123]
	s_waitcnt vmcnt(0)
	v_mov_b32_e32 v116, v168
	v_mov_b32_e32 v117, v170
	v_pk_mul_f32 v[108:109], v[112:113], v[108:109]
	v_lshlrev_b32_e32 v113, 16, v125
	v_lshlrev_b32_e32 v112, 16, v124
	v_pk_fma_f32 v[110:111], v[116:117], v[102:103], v[110:111]
	v_mov_b32_e32 v166, v165
	v_pk_mul_f32 v[110:111], v[110:111], v[112:113]
	v_mov_b32_e32 v162, v161
	v_pk_mul_f32 v[112:113], v[166:167], v[26:27]
	v_mov_b32_e32 v170, v169
	v_pk_fma_f32 v[42:43], v[162:163], v[42:43], v[112:113]
	v_and_b32_e32 v115, 0xffff0000, v125
	v_and_b32_e32 v114, 0xffff0000, v124
	v_pk_fma_f32 v[42:43], v[170:171], v[10:11], v[42:43]
	v_bfe_u32 v46, v110, 16, 1
	v_pk_mul_f32 v[42:43], v[42:43], v[114:115]
	v_bfe_u32 v48, v111, 16, 1
	v_bfe_u32 v14, v43, 16, 1
	v_bfe_u32 v16, v42, 16, 1
	v_add3_u32 v16, v42, v16, s72
	v_add3_u32 v14, v43, v14, s72
	v_bfe_u32 v42, v12, 16, 1
	v_bfe_u32 v43, v13, 16, 1
	v_bfe_u32 v18, v109, 16, 1
	v_bfe_u32 v20, v108, 16, 1
	v_add3_u32 v48, v111, v48, s72
	v_add3_u32 v46, v110, v46, s72
	v_add3_u32 v13, v13, v43, s72
	v_add3_u32 v12, v12, v42, s72
	v_add3_u32 v20, v108, v20, s72
	v_add3_u32 v18, v109, v18, s72
	v_lshrrev_b32_e32 v12, 16, v12
	v_lshrrev_b32_e32 v13, 16, v13
	v_lshrrev_b32_e32 v42, 16, v46
	v_lshrrev_b32_e32 v43, 16, v48
	v_and_or_b32 v111, v14, s55, v43
	v_and_or_b32 v110, v16, s55, v42
	v_and_or_b32 v109, v18, s55, v13
	v_and_or_b32 v108, v20, s55, v12
	v_add_co_u32_e32 v12, vcc, s0, v96
	global_store_dwordx4 v[24:25], v[108:111], off offset:1536
	s_nop 0
	v_addc_co_u32_e32 v13, vcc, 0, v97, vcc
	v_mov_b64_e32 v[108:109], v[250:251]
	v_mov_b64_e32 v[110:111], v[252:253]
	global_load_dwordx4 v[112:115], v[50:51], off
	global_load_dwordx4 v[122:125], v[50:51], off offset:3072
	global_load_dwordx4 v[126:129], v[52:53], off
	global_load_dwordx4 v[130:133], v[54:55], off
	global_load_dwordx4 v[156:159], v[50:51], off offset:16
	global_load_dwordx4 v[160:163], v[50:51], off offset:3088
	global_load_dwordx4 v[164:167], v[52:53], off offset:16
	global_load_dwordx4 v[168:171], v[54:55], off offset:16
	v_lshlrev_b32_e32 v12, 16, v6
	v_lshlrev_b32_e32 v13, 16, v7
	v_and_b32_e32 v20, 0xffff0000, v19
	v_and_b32_e32 v6, 0xffff0000, v6
	v_and_b32_e32 v7, 0xffff0000, v7
	v_lshlrev_b32_e32 v42, 16, v8
	v_lshlrev_b32_e32 v43, 16, v9
	v_and_b32_e32 v8, 0xffff0000, v8
	v_and_b32_e32 v9, 0xffff0000, v9
	s_mov_b32 s0, 0x6007000
	v_and_b32_e32 v48, 0xffff0000, v2
	v_and_b32_e32 v46, 0xffff0000, v4
	v_lshlrev_b32_e32 v4, 16, v4
	v_lshlrev_b32_e32 v2, 16, v2
	s_waitcnt vmcnt(8)
	v_lshlrev_b32_e32 v116, 16, v108
	v_and_b32_e32 v108, 0xffff0000, v108
	v_mul_f32_e32 v14, 0xbfb8aa3b, v116
	v_exp_f32_e32 v14, v14
	v_mul_f32_e32 v16, 0xbfb8aa3b, v108
	v_exp_f32_e32 v16, v16
	v_lshlrev_b32_e32 v117, 16, v109
	v_add_f32_e32 v14, 1.0, v14
	v_rcp_f32_e32 v134, v14
	v_add_f32_e32 v14, 1.0, v16
	v_rcp_f32_e32 v18, v14
	v_mul_f32_e32 v14, 0xbfb8aa3b, v117
	v_exp_f32_e32 v14, v14
	v_and_b32_e32 v109, 0xffff0000, v109
	s_waitcnt vmcnt(6)
	v_mov_b32_e32 v174, v122
	v_mov_b32_e32 v175, v124
	v_add_f32_e32 v14, 1.0, v14
	v_rcp_f32_e32 v135, v14
	v_mul_f32_e32 v14, 0xbfb8aa3b, v109
	v_exp_f32_e32 v14, v14
	v_mov_b32_e32 v172, v112
	v_mov_b32_e32 v173, v114
	v_pk_mul_f32 v[120:121], v[174:175], v[120:121]
	v_add_f32_e32 v14, 1.0, v14
	v_pk_fma_f32 v[44:45], v[172:173], v[44:45], v[120:121]
	s_waitcnt vmcnt(5)
	v_mov_b32_e32 v120, v126
	v_mov_b32_e32 v121, v128
	v_pk_fma_f32 v[12:13], v[120:121], v[12:13], v[44:45]
	s_waitcnt vmcnt(4)
	v_mov_b32_e32 v44, v130
	v_mov_b32_e32 v45, v132
	v_pk_add_f32 v[12:13], v[44:45], v[12:13]
	v_pk_mul_f32 v[44:45], v[134:135], v[116:117]
	v_mov_b32_e32 v124, v123
	v_pk_mul_f32 v[12:13], v[12:13], v[44:45]
	v_rcp_f32_e32 v19, v14
	v_pk_mul_f32 v[12:13], v[12:13], v[20:21]
	v_mov_b32_e32 v114, v113
	v_pk_mul_f32 v[20:21], v[124:125], v[118:119]
	v_mov_b32_e32 v128, v127
	v_pk_fma_f32 v[20:21], v[114:115], v[34:35], v[20:21]
	v_mov_b32_e32 v132, v131
	v_pk_fma_f32 v[6:7], v[128:129], v[6:7], v[20:21]
	v_pk_mul_f32 v[18:19], v[18:19], v[108:109]
	v_pk_add_f32 v[6:7], v[132:133], v[6:7]
	v_and_b32_e32 v20, 0xffff0000, v110
	v_pk_mul_f32 v[6:7], v[18:19], v[6:7]
	v_and_b32_e32 v19, 0xffff0000, v101
	v_and_b32_e32 v18, 0xffff0000, v99
	v_pk_mul_f32 v[6:7], v[6:7], v[18:19]
	v_lshlrev_b32_e32 v18, 16, v110
	v_mul_f32_e32 v14, 0xbfb8aa3b, v18
	v_exp_f32_e32 v14, v14
	v_mul_f32_e32 v16, 0xbfb8aa3b, v20
	v_exp_f32_e32 v16, v16
	v_lshlrev_b32_e32 v19, 16, v111
	v_add_f32_e32 v14, 1.0, v14
	v_rcp_f32_e32 v34, v14
	v_add_f32_e32 v14, 1.0, v16
	v_mul_f32_e32 v16, 0xbfb8aa3b, v19
	v_exp_f32_e32 v16, v16
	v_and_b32_e32 v21, 0xffff0000, v111
	s_waitcnt vmcnt(2)
; __device__ __forceinline__ float silu_f(float v) { return v * __builtin_amdgcn_rcpf(1.f + __builtin_amdgcn_exp2f(-1.4426950408889634f * v)); }
; __device__ __forceinline__ v4u pack8(const float (&f)[8]) { v4u o; o.x = pk2(f[0], f[1]); o.y = pk2(f[2], f[3]); o.z = pk2(f[4], f[5]); o.w = pk2(f[6], f[7]); return o; }
; __device__ __forceinline__ void phase_combine(int l, LAS unsigned char* lds, int G) {
;     ...
;         for (int r = 0; r < 4; ++r) {
;             const bf16r* pr = base + (size_t)r * DIN; const size_t row = row0 + tl0 + r;
;             bf16r* yrow = Y + row * DMODEL + c;
;             float g[8], o[8], y[8];
;             { unpack8(*(const v4u*)(pr + C_BG), g); float xa[8], xb[8], xc[8]; unpack8(xw[r], xa); unpack8(xw[r + 1], xb); unpack8(xw[r + 2], xc);
; #pragma unroll
;               for (int e = 0; e < 8; ++e) { const float x0 = cw[c + e] * xa[e] + cw[768 + c + e] * xb[e] + cw[1536 + c + e] * xc[e] + cbv[c + e];
;                   y[e] = silu_f(g[e]) * x0 * bf1(yt[(c + e) * YTP + tl0 + r]); }
;               *(v4u*)(yrow + 256) = pack8(y); }
;             { unpack8(*(const v4u*)(pr + C_DP), o);
; #pragma unroll
;               for (int e = 0; e < 8; ++e) y[e] = o[e] * (scw[c + e] * uw[r][e] + scw[256 + c + e] * uw[r + 1][e] + scw[512 + c + e] * uw[r + 2][e]);
;               *(v4u*)(yrow + 768) = pack8(y); }
;         }
;         __syncthreads();
;     }
	v_mov_b32_e32 v98, v160
	v_mov_b32_e32 v99, v162
	v_add_f32_e32 v16, 1.0, v16
	v_rcp_f32_e32 v35, v16
	v_and_b32_e32 v16, 0xffff0000, v15
	v_mul_f32_e32 v15, 0xbfb8aa3b, v21
	v_exp_f32_e32 v15, v15
	v_mov_b32_e32 v44, v156
	v_mov_b32_e32 v45, v158
	v_pk_mul_f32 v[28:29], v[98:99], v[28:29]
	v_pk_mul_f32 v[18:19], v[34:35], v[18:19]
	v_pk_fma_f32 v[28:29], v[44:45], v[32:33], v[28:29]
	s_waitcnt vmcnt(1)
	v_mov_b32_e32 v32, v164
	v_mov_b32_e32 v33, v166
	v_pk_fma_f32 v[28:29], v[32:33], v[42:43], v[28:29]
	s_waitcnt vmcnt(0)
	v_mov_b32_e32 v32, v168
	v_mov_b32_e32 v33, v170
	v_pk_add_f32 v[28:29], v[32:33], v[28:29]
	v_add_f32_e32 v15, 1.0, v15
	v_rcp_f32_e32 v14, v14
	v_pk_mul_f32 v[18:19], v[18:19], v[28:29]
	v_mov_b32_e32 v162, v161
	v_rcp_f32_e32 v15, v15
	v_pk_mul_f32 v[16:17], v[18:19], v[16:17]
	v_mov_b32_e32 v158, v157
	v_pk_mul_f32 v[18:19], v[162:163], v[22:23]
	v_mov_b32_e32 v166, v165
	v_pk_fma_f32 v[18:19], v[158:159], v[30:31], v[18:19]
	v_mov_b32_e32 v170, v169
	v_pk_fma_f32 v[8:9], v[166:167], v[8:9], v[18:19]
	v_pk_mul_f32 v[14:15], v[14:15], v[20:21]
	v_pk_add_f32 v[8:9], v[170:171], v[8:9]
	v_bfe_u32 v18, v7, 16, 1
	v_pk_mul_f32 v[8:9], v[14:15], v[8:9]
	v_and_b32_e32 v15, 0xffff0000, v49
	v_and_b32_e32 v14, 0xffff0000, v47
	v_pk_mul_f32 v[8:9], v[8:9], v[14:15]
	v_bfe_u32 v19, v6, 16, 1
	v_bfe_u32 v14, v9, 16, 1
	v_bfe_u32 v15, v8, 16, 1
	v_add3_u32 v6, v6, v19, s72
	v_add3_u32 v7, v7, v18, s72
	v_add3_u32 v8, v8, v15, s72
	v_add3_u32 v9, v9, v14, s72
	v_bfe_u32 v14, v12, 16, 1
	v_bfe_u32 v15, v13, 16, 1
	v_bfe_u32 v18, v16, 16, 1
	v_bfe_u32 v19, v17, 16, 1
	v_add3_u32 v17, v17, v19, s72
	v_add3_u32 v16, v16, v18, s72
	v_add3_u32 v13, v13, v15, s72
	v_add3_u32 v12, v12, v14, s72
	v_lshrrev_b32_e32 v12, 16, v12
	v_lshrrev_b32_e32 v13, 16, v13
	v_lshrrev_b32_e32 v14, 16, v16
	v_lshrrev_b32_e32 v15, 16, v17
	v_and_or_b32 v9, v9, s55, v15
	v_and_or_b32 v8, v8, s55, v14
	v_and_or_b32 v7, v7, s55, v13
	v_and_or_b32 v6, v6, s55, v12
	global_store_dwordx4 v[24:25], v[6:9], off offset:2560
	v_and_b32_e32 v49, 0xffff0000, v3
	v_and_b32_e32 v47, 0xffff0000, v5
	v_add_co_u32_e32 v6, vcc, s0, v96
	v_lshlrev_b32_e32 v5, 16, v5
	s_nop 0
	v_addc_co_u32_e32 v7, vcc, 0, v97, vcc
	v_mov_b64_e32 v[6:7], v[244:245]
	v_mov_b64_e32 v[8:9], v[254:255]
	s_nop 0
	global_load_dwordx4 v[12:15], v[56:57], off
	global_load_dwordx4 v[16:19], v[56:57], off offset:1024
	global_load_dwordx4 v[20:23], v[56:57], off offset:2048
	global_load_dwordx4 v[28:31], v[56:57], off offset:16
	global_load_dwordx4 v[32:35], v[56:57], off offset:1040
	global_load_dwordx4 v[42:45], v[56:57], off offset:2064
	v_lshlrev_b32_e32 v3, 16, v3
	v_readlane_b32 s0, v247, 27
	s_add_i32 s14, s14, s0
	v_readlane_b32 s0, v247, 21
	v_readlane_b32 s1, v247, 22
	s_cmpk_lt_i32 s15, 0x200
	s_waitcnt vmcnt(6)
	v_lshlrev_b32_e32 v97, 16, v7
	s_waitcnt vmcnt(5)
	v_mov_b32_e32 v98, v12
	s_waitcnt vmcnt(4)
	v_mov_b32_e32 v100, v16
	v_mov_b32_e32 v101, v18
	v_mov_b32_e32 v18, v17
	v_mov_b32_e32 v99, v14
	v_pk_mul_f32 v[100:101], v[100:101], v[106:107]
	v_mov_b32_e32 v14, v13
	v_pk_mul_f32 v[12:13], v[18:19], v[104:105]
	s_waitcnt vmcnt(1)
	v_mov_b32_e32 v16, v32
	v_mov_b32_e32 v17, v34
	v_mov_b32_e32 v34, v33
	v_pk_fma_f32 v[40:41], v[98:99], v[40:41], v[100:101]
	v_mov_b32_e32 v99, v22
	v_pk_fma_f32 v[12:13], v[14:15], v[38:39], v[12:13]
	v_mov_b32_e32 v22, v21
	v_mov_b32_e32 v14, v28
	v_mov_b32_e32 v15, v30
	v_pk_mul_f32 v[16:17], v[16:17], v[102:103]
	v_mov_b32_e32 v30, v29
	v_pk_mul_f32 v[10:11], v[34:35], v[10:11]
	v_lshlrev_b32_e32 v96, 16, v6
	v_and_b32_e32 v7, 0xffff0000, v7
	v_and_b32_e32 v6, 0xffff0000, v6
	v_pk_fma_f32 v[12:13], v[22:23], v[48:49], v[12:13]
	v_pk_fma_f32 v[14:15], v[14:15], v[36:37], v[16:17]
	s_waitcnt vmcnt(0)
	v_mov_b32_e32 v17, v44
	v_pk_fma_f32 v[10:11], v[30:31], v[26:27], v[10:11]
	v_mov_b32_e32 v44, v43
	v_mov_b32_e32 v98, v20
	v_pk_mul_f32 v[6:7], v[12:13], v[6:7]
	v_lshlrev_b32_e32 v13, 16, v9
	v_lshlrev_b32_e32 v12, 16, v8
	v_and_b32_e32 v9, 0xffff0000, v9
	v_and_b32_e32 v8, 0xffff0000, v8
	v_mov_b32_e32 v16, v42
	v_pk_fma_f32 v[10:11], v[44:45], v[46:47], v[10:11]
	v_pk_fma_f32 v[2:3], v[98:99], v[2:3], v[40:41]
	v_pk_fma_f32 v[4:5], v[16:17], v[4:5], v[14:15]
	v_pk_mul_f32 v[8:9], v[10:11], v[8:9]
	v_pk_mul_f32 v[2:3], v[2:3], v[96:97]
	v_pk_mul_f32 v[4:5], v[4:5], v[12:13]
	v_bfe_u32 v10, v9, 16, 1
	v_bfe_u32 v11, v8, 16, 1
	v_bfe_u32 v12, v7, 16, 1
	v_bfe_u32 v13, v6, 16, 1
	v_add3_u32 v6, v6, v13, s72
	v_add3_u32 v7, v7, v12, s72
	v_add3_u32 v8, v8, v11, s72
	v_add3_u32 v9, v9, v10, s72
	v_bfe_u32 v10, v2, 16, 1
	v_bfe_u32 v11, v3, 16, 1
	v_bfe_u32 v12, v4, 16, 1
	v_bfe_u32 v13, v5, 16, 1
	v_add3_u32 v5, v5, v13, s72
	v_add3_u32 v4, v4, v12, s72
	v_add3_u32 v3, v3, v11, s72
	v_add3_u32 v2, v2, v10, s72
	v_lshl_add_u64 v[92:93], v[92:93], 0, s[0:1]
	v_readlane_b32 s0, v247, 48
	v_lshrrev_b32_e32 v2, 16, v2
	v_lshrrev_b32_e32 v3, 16, v3
	v_lshrrev_b32_e32 v4, 16, v4
	v_lshrrev_b32_e32 v5, 16, v5
	v_readlane_b32 s1, v247, 49
	v_and_or_b32 v5, v9, s55, v5
	v_and_or_b32 v4, v8, s55, v4
	v_and_or_b32 v3, v7, s55, v3
	v_and_or_b32 v2, v6, s55, v2
	v_lshl_add_u64 v[94:95], v[94:95], 0, s[0:1]
	global_store_dwordx4 v[24:25], v[2:5], off offset:3584
	s_barrier
	s_cbranch_scc0 .LBB0_616
; __device__ __forceinline__ void phase_combine(int l, LAS unsigned char* lds, int G) {
;     ...
;     for (int tile = blockIdx.x; tile < MROWS / 64; tile += G) {
;         const int b = tile >> 6, t0 = (tile & 63) * 64; const size_t row0 = (size_t)tile * 64;
;         const int tl0 = 4 * rgp, tb = t0 + tl0;
;         const bf16r* base = PROJ + (row0 + tl0) * DIN + c;
;         v4u xw[6]; float uw[6][8];
; #pragma unroll
;         for (int q = 0; q < 6; ++q) { const int t = tb + q - 1; const bool ok = (t >= 0) && (t < SEQ);
;             v4u a = (v4u){0u, 0u, 0u, 0u}, g = a;
;             if (ok) { const bf16r* pr = base + (long)(q - 1) * DIN; a = *(const v4u*)(pr + C_BP); g = *(const v4u*)(pr + C_DP + 256); }
;             xw[q] = a; unpack8(g, uw[q]); }
.LBB0_604:
	s_and_b32 s16, s14, 0xfc0
	v_add_u32_e32 v3, s16, v137
	v_cmp_gt_u32_e32 vcc, s75, v3
	v_mov_b32_e32 v34, 0
	v_lshl_add_u64 v[96:97], v[92:93], 0, v[90:91]
	s_mov_b32 s99, 0
	s_mov_b32 s98, 0x6000c00
	v_lshl_add_u64 v[210:211], v[96:97], 0, s[98:99]
	global_load_dwordx4 v[210:213], v[210:211], off
	s_mov_b32 s98, 0x6001600
	v_lshl_add_u64 v[214:215], v[96:97], 0, s[98:99]
	global_load_dwordx4 v[214:217], v[214:215], off
	s_mov_b32 s98, 0x6002a00
	v_lshl_add_u64 v[228:229], v[96:97], 0, s[98:99]
	global_load_dwordx4 v[228:231], v[228:229], off
	s_mov_b32 s98, 0x6003400
	v_lshl_add_u64 v[232:233], v[96:97], 0, s[98:99]
	global_load_dwordx4 v[232:235], v[232:233], off
	s_mov_b32 s98, 0x6004800
	v_lshl_add_u64 v[236:237], v[96:97], 0, s[98:99]
	global_load_dwordx4 v[236:239], v[236:237], off
	s_mov_b32 s98, 0x6005200
	v_lshl_add_u64 v[240:241], v[96:97], 0, s[98:99]
	global_load_dwordx4 v[240:243], v[240:241], off
	s_mov_b32 s98, 0x6006600
	v_lshl_add_u64 v[250:251], v[96:97], 0, s[98:99]
	global_load_dwordx4 v[250:253], v[250:251], off
	s_mov_b32 s98, 0x6007000
	v_lshl_add_u64 v[244:245], v[96:97], 0, s[98:99]
	v_lshl_add_u64 v[254:255], v[96:97], 0, s[98:99]
	global_load_dwordx2 v[244:245], v[244:245], off
	global_load_dwordx2 v[254:255], v[254:255], off offset:8
	v_mov_b32_e32 v30, 0
	v_mov_b32_e32 v31, 0
	v_mov_b32_e32 v32, 0
	v_mov_b32_e32 v33, 0
	v_mov_b32_e32 v14, 0
	v_mov_b32_e32 v15, 0
	v_mov_b32_e32 v16, 0
	v_mov_b32_e32 v17, 0
	s_and_saveexec_b64 s[0:1], vcc
	s_cbranch_execz .LBB0_606
	v_add_co_u32_e32 v4, vcc, 0x5ffe000, v96
	s_nop 1
	v_addc_co_u32_e32 v5, vcc, 0, v97, vcc
	v_add_co_u32_e32 v6, vcc, 0x5fff000, v96
	s_nop 1
	v_addc_co_u32_e32 v7, vcc, 0, v97, vcc
	global_load_dwordx4 v[14:17], v[4:5], off offset:2048
	global_load_dwordx4 v[30:33], v[6:7], off offset:2560

; #define LAS __attribute__((address_space(3)))
; __global__ void __launch_bounds__(NTHR, 2) hymba_fwd(Params Pk) {
;     extern __shared__ __attribute__((aligned(16))) unsigned char lds_raw[];
;     LAS unsigned char* lds = (LAS unsigned char*)lds_raw;
	.amdhsa_kernel _Z9hymba_fwd6Params
		.amdhsa_group_segment_fixed_size 0
		.amdhsa_private_segment_fixed_size 0
		.amdhsa_kernarg_size 560
		.amdhsa_user_sgpr_count 2
		.amdhsa_user_sgpr_dispatch_ptr 0
		.amdhsa_user_sgpr_queue_ptr 0
		.amdhsa_user_sgpr_kernarg_segment_ptr 1
		.amdhsa_user_sgpr_dispatch_id 0
		.amdhsa_user_sgpr_kernarg_preload_length 0
		.amdhsa_user_sgpr_kernarg_preload_offset 0
		.amdhsa_user_sgpr_private_segment_size 0
		.amdhsa_uses_dynamic_stack 0
		.amdhsa_enable_private_segment 0
		.amdhsa_system_sgpr_workgroup_id_x 1
		.amdhsa_system_sgpr_workgroup_id_y 0
		.amdhsa_system_sgpr_workgroup_id_z 0
		.amdhsa_system_sgpr_workgroup_info 0
		.amdhsa_system_vgpr_workitem_id 2
		.amdhsa_next_free_vgpr 256
		.amdhsa_next_free_sgpr 100
		.amdhsa_accum_offset 256
		.amdhsa_reserve_vcc 1
		.amdhsa_float_round_mode_32 0
		.amdhsa_float_round_mode_16_64 0
		.amdhsa_float_denorm_mode_32 3
		.amdhsa_float_denorm_mode_16_64 3
		.amdhsa_dx10_clamp 1
		.amdhsa_ieee_mode 1
		.amdhsa_fp16_overflow 0
		.amdhsa_tg_split 0
		.amdhsa_exception_fp_ieee_invalid_op 0
		.amdhsa_exception_fp_denorm_src 0
		.amdhsa_exception_fp_ieee_div_zero 0
		.amdhsa_exception_fp_ieee_overflow 0
		.amdhsa_exception_fp_ieee_underflow 0
		.amdhsa_exception_fp_ieee_inexact 0
		.amdhsa_exception_int_div_zero 0
	.end_amdhsa_kernel

; #define LAS __attribute__((address_space(3)))
; __global__ void __launch_bounds__(NTHR, 2) hymba_fwd(Params Pk) {
;     extern __shared__ __attribute__((aligned(16))) unsigned char lds_raw[];
;     LAS unsigned char* lds = (LAS unsigned char*)lds_raw;
amdhsa.kernels:
  - .agpr_count:     0
    .args:
      - .offset:         0
        .size:           304
        .value_kind:     by_value
      - .offset:         304
        .size:           4
        .value_kind:     hidden_block_count_x
      - .offset:         308
        .size:           4
        .value_kind:     hidden_block_count_y
      - .offset:         312
        .size:           4
        .value_kind:     hidden_block_count_z
      - .offset:         316
        .size:           2
        .value_kind:     hidden_group_size_x
      - .offset:         318
        .size:           2
        .value_kind:     hidden_group_size_y
      - .offset:         320
        .size:           2
        .value_kind:     hidden_group_size_z
      - .offset:         322
        .size:           2
        .value_kind:     hidden_remainder_x
      - .offset:         324
        .size:           2
        .value_kind:     hidden_remainder_y
      - .offset:         326
        .size:           2
        .value_kind:     hidden_remainder_z
      - .offset:         344
        .size:           8
        .value_kind:     hidden_global_offset_x
      - .offset:         352
        .size:           8
        .value_kind:     hidden_global_offset_y
      - .offset:         360
        .size:           8
        .value_kind:     hidden_global_offset_z
      - .offset:         368
        .size:           2
        .value_kind:     hidden_grid_dims
      - .offset:         392
        .size:           8
        .value_kind:     hidden_multigrid_sync_arg
      - .offset:         424
        .size:           4
        .value_kind:     hidden_dynamic_lds_size
    .group_segment_fixed_size: 0
    .kernarg_segment_align: 8
    .kernarg_segment_size: 560
    .language:       OpenCL C
    .language_version:
      - 2
      - 0
    .max_flat_workgroup_size: 512
    .name:           _Z9hymba_fwd6Params
    .private_segment_fixed_size: 0
    .sgpr_count:     106
    .sgpr_spill_count: 152
    .symbol:         _Z9hymba_fwd6Params.kd
    .uniform_work_group_size: 1
    .uses_dynamic_stack: false
    .vgpr_count:     256
    .vgpr_spill_count: 0
    .wavefront_size: 64
